# non-temporal stores for the f32 residual rows written by the GLU GEMM epilogue, on top of the combine-phase load hints (re-measure)
# baseline (speedup 1.0000x reference)
;     DI void operator()(const f32x4 (&acc)[2][2][4][2], const Unit& u, int wr, int wc, int fr, int fq) const {
;         const int trow = u.pm * BM; const bool lat = trow < ML;
;         const float* src = lat ? src_l : src_c; float* dst = lat ? dst_l : dst_c;
;         const int rbase = (lat ? trow : trow - ML) + wr * 64 + fr; const int grow = lat ? (trow >> 12) : 16;
;         const float* gp = gate + (size_t)grow * 6144;
;         const int col0 = u.pn * BM + wc * 32 + 8 * fq;
; #pragma unroll
;         for (int bj = 0; bj < 2; ++bj) {
;             const int col = (col0 + bj * HALF) >> 1;
;             const f32x4 g0 = *(const f32x4*)(gp + col);
; #pragma unroll
;             for (int ai = 0; ai < 2; ++ai)
; #pragma unroll
;                 for (int m = 0; m < 4; ++m) { const size_t off = (size_t)(rbase + ai * HALF + m * 16) * D + col;
;                     const f32x4 x0 = *(const f32x4*)(src + off); const f32x4 za = acc[ai][bj][m][0], zb = acc[ai][bj][m][1]; f32x4 o;
; #pragma unroll
;                     for (int q = 0; q < 4; ++q) o[q] = za[q] / (1.f + __expf(-zb[q]));
;                     *(f32x4*)(dst + off) = x0 + g0 * o; }
.LBB0_669:
	s_lshl_b32 s12, s30, 8
	s_add_i32 s13, s12, 0xffff0000
	s_cmpk_lt_i32 s30, 0x100
	s_cselect_b32 s12, s12, s13
	s_cselect_b32 s69, s11, s15
	s_cselect_b32 s68, s10, s14
	s_cselect_b32 s67, s19, s3
	s_cselect_b32 s66, s18, s2
	v_add_u32_e32 v158, s12, v160
	s_min_i32 s12, s30, 0x100
	v_lshl_or_b32 v84, s31, 8, v162
	s_ashr_i32 s12, s12, 4
	v_ashrrev_i32_e32 v156, 1, v84
	v_ashrrev_i32_e32 v159, 31, v158
	s_mul_hi_i32 s13, s12, 0x6000
	s_mulk_i32 s12, 0x6000
	v_ashrrev_i32_e32 v157, 31, v156
	v_lshlrev_b64 v[152:153], 10, v[158:159]
	s_add_u32 s26, s79, s12
	v_lshl_add_u64 v[152:153], v[152:153], 0, v[156:157]
	s_addc_u32 s27, s80, s13
	v_lshlrev_b64 v[154:155], 2, v[152:153]
	v_lshl_add_u64 v[142:143], v[156:157], 2, s[26:27]
	v_lshl_add_u64 v[152:153], s[68:69], 0, v[154:155]
	s_mov_b64 s[12:13], 0x10000
	global_load_dwordx4 v[216:219], v[142:143], off
	global_load_dwordx4 v[220:223], v[142:143], off offset:256
	v_lshl_add_u64 v[234:235], s[66:67], 0, v[154:155]
	global_load_dwordx4 v[176:179], v[152:153], off
	global_load_dwordx4 v[180:183], v[152:153], off offset:256
	v_lshl_add_u64 v[152:153], v[152:153], 0, s[12:13]
	global_load_dwordx4 v[184:187], v[152:153], off
	global_load_dwordx4 v[188:191], v[152:153], off offset:256
	v_lshl_add_u64 v[152:153], v[152:153], 0, s[12:13]
	global_load_dwordx4 v[192:195], v[152:153], off
	global_load_dwordx4 v[196:199], v[152:153], off offset:256
	v_lshl_add_u64 v[152:153], v[152:153], 0, s[12:13]
	global_load_dwordx4 v[200:203], v[152:153], off
	global_load_dwordx4 v[204:207], v[152:153], off offset:256
	v_lshl_add_u64 v[152:153], v[152:153], 0, s[12:13]
	v_lshl_add_u64 v[152:153], v[152:153], 0, s[12:13]
	v_lshl_add_u64 v[152:153], v[152:153], 0, s[12:13]
	v_lshl_add_u64 v[152:153], v[152:153], 0, s[12:13]
	v_lshl_add_u64 v[152:153], v[152:153], 0, s[12:13]
	v_mul_f32_e32 v128, 0xbfb8aa3b, v128
	v_mul_f32_e32 v129, 0xbfb8aa3b, v129
	v_exp_f32_e32 v128, v128
	v_exp_f32_e32 v129, v129
	v_add_f32_e32 v128, 1.0, v128
	v_add_f32_e32 v129, 1.0, v129
	v_div_scale_f32 v224, s[26:27], v128, v128, v124
	v_div_scale_f32 v229, s[26:27], v129, v129, v125
	v_rcp_f32_e32 v225, v224
	v_rcp_f32_e32 v230, v229
	v_fma_f32 v226, -v224, v225, 1.0
	v_fma_f32 v231, -v229, v230, 1.0
	v_fmac_f32_e32 v225, v226, v225
	v_fmac_f32_e32 v230, v231, v230
	v_div_scale_f32 v226, vcc, v124, v128, v124
	v_mul_f32_e32 v227, v226, v225
	v_fma_f32 v228, -v224, v227, v226
	v_fmac_f32_e32 v227, v228, v225
	v_fma_f32 v224, -v224, v227, v226
	v_div_fmas_f32 v224, v224, v225, v227
	v_div_fixup_f32 v124, v224, v128, v124
	v_div_scale_f32 v231, vcc, v125, v129, v125
	v_mul_f32_e32 v232, v231, v230
	v_fma_f32 v233, -v229, v232, v231
	v_fmac_f32_e32 v232, v233, v230
	v_fma_f32 v229, -v229, v232, v231
	v_div_fmas_f32 v229, v229, v230, v232
	v_div_fixup_f32 v125, v229, v129, v125
	v_mul_f32_e32 v130, 0xbfb8aa3b, v130
	v_mul_f32_e32 v131, 0xbfb8aa3b, v131
	v_exp_f32_e32 v130, v130
	v_exp_f32_e32 v131, v131
	v_add_f32_e32 v130, 1.0, v130
	v_add_f32_e32 v131, 1.0, v131
	v_div_scale_f32 v224, s[26:27], v130, v130, v126
	v_div_scale_f32 v229, s[26:27], v131, v131, v127
	v_rcp_f32_e32 v225, v224
	v_rcp_f32_e32 v230, v229
	v_fma_f32 v226, -v224, v225, 1.0
	v_fma_f32 v231, -v229, v230, 1.0
	v_fmac_f32_e32 v225, v226, v225
	v_fmac_f32_e32 v230, v231, v230
	v_div_scale_f32 v226, vcc, v126, v130, v126
	v_mul_f32_e32 v227, v226, v225
	v_fma_f32 v228, -v224, v227, v226
	v_fmac_f32_e32 v227, v228, v225
	v_fma_f32 v224, -v224, v227, v226
	v_div_fmas_f32 v224, v224, v225, v227
	v_div_fixup_f32 v126, v224, v130, v126
	v_div_scale_f32 v231, vcc, v127, v131, v127
	v_mul_f32_e32 v232, v231, v230
	v_fma_f32 v233, -v229, v232, v231
	v_fmac_f32_e32 v232, v233, v230
	v_fma_f32 v229, -v229, v232, v231
	v_div_fmas_f32 v229, v229, v230, v232
	v_div_fixup_f32 v127, v229, v131, v127
	v_mul_f32_e32 v60, 0xbfb8aa3b, v60
	v_mul_f32_e32 v61, 0xbfb8aa3b, v61
	v_exp_f32_e32 v60, v60
	v_exp_f32_e32 v61, v61
	v_add_f32_e32 v60, 1.0, v60
	v_add_f32_e32 v61, 1.0, v61
	v_div_scale_f32 v224, s[26:27], v60, v60, v56
	v_div_scale_f32 v229, s[26:27], v61, v61, v57
	v_rcp_f32_e32 v225, v224
	v_rcp_f32_e32 v230, v229
	v_fma_f32 v226, -v224, v225, 1.0
	v_fma_f32 v231, -v229, v230, 1.0
	v_fmac_f32_e32 v225, v226, v225
	v_fmac_f32_e32 v230, v231, v230
	v_div_scale_f32 v226, vcc, v56, v60, v56
	v_mul_f32_e32 v227, v226, v225
	v_fma_f32 v228, -v224, v227, v226
	v_fmac_f32_e32 v227, v228, v225
	v_fma_f32 v224, -v224, v227, v226
	v_div_fmas_f32 v224, v224, v225, v227
	v_div_fixup_f32 v56, v224, v60, v56
	v_div_scale_f32 v231, vcc, v57, v61, v57
	v_mul_f32_e32 v232, v231, v230
	v_fma_f32 v233, -v229, v232, v231
	v_fmac_f32_e32 v232, v233, v230
	v_fma_f32 v229, -v229, v232, v231
	v_div_fmas_f32 v229, v229, v230, v232
	v_div_fixup_f32 v57, v229, v61, v57
	v_mul_f32_e32 v62, 0xbfb8aa3b, v62
	v_mul_f32_e32 v63, 0xbfb8aa3b, v63
	v_exp_f32_e32 v62, v62
	v_exp_f32_e32 v63, v63
	v_add_f32_e32 v62, 1.0, v62
	v_add_f32_e32 v63, 1.0, v63
	v_div_scale_f32 v224, s[26:27], v62, v62, v58
	v_div_scale_f32 v229, s[26:27], v63, v63, v59
	v_rcp_f32_e32 v225, v224
	v_rcp_f32_e32 v230, v229
	v_fma_f32 v226, -v224, v225, 1.0
	v_fma_f32 v231, -v229, v230, 1.0
	v_fmac_f32_e32 v225, v226, v225
	v_fmac_f32_e32 v230, v231, v230
	v_div_scale_f32 v226, vcc, v58, v62, v58
	v_mul_f32_e32 v227, v226, v225
	v_fma_f32 v228, -v224, v227, v226
	v_fmac_f32_e32 v227, v228, v225
	v_fma_f32 v224, -v224, v227, v226
	v_div_fmas_f32 v224, v224, v225, v227
	v_div_fixup_f32 v58, v224, v62, v58
	v_div_scale_f32 v231, vcc, v59, v63, v59
	v_mul_f32_e32 v232, v231, v230
	v_fma_f32 v233, -v229, v232, v231
	v_fmac_f32_e32 v232, v233, v230
;     DI void operator()(const f32x4 (&acc)[2][2][4][2], const Unit& u, int wr, int wc, int fr, int fq) const {
;     ...
;                 for (int m = 0; m < 4; ++m) { const size_t off = (size_t)(rbase + ai * HALF + m * 16) * D + col;
;                     const f32x4 x0 = *(const f32x4*)(src + off); const f32x4 za = acc[ai][bj][m][0], zb = acc[ai][bj][m][1]; f32x4 o;
; #pragma unroll
;                     for (int q = 0; q < 4; ++q) o[q] = za[q] / (1.f + __expf(-zb[q]));
;                     *(f32x4*)(dst + off) = x0 + g0 * o; }
	v_fma_f32 v229, -v229, v232, v231
	v_div_fmas_f32 v229, v229, v230, v232
	v_div_fixup_f32 v59, v229, v63, v59
	v_mul_f32_e32 v120, 0xbfb8aa3b, v120
	v_mul_f32_e32 v121, 0xbfb8aa3b, v121
	v_exp_f32_e32 v120, v120
	v_exp_f32_e32 v121, v121
	v_add_f32_e32 v120, 1.0, v120
	v_add_f32_e32 v121, 1.0, v121
	v_div_scale_f32 v224, s[26:27], v120, v120, v116
	v_div_scale_f32 v229, s[26:27], v121, v121, v117
	v_rcp_f32_e32 v225, v224
	v_rcp_f32_e32 v230, v229
	v_fma_f32 v226, -v224, v225, 1.0
	v_fma_f32 v231, -v229, v230, 1.0
	v_fmac_f32_e32 v225, v226, v225
	v_fmac_f32_e32 v230, v231, v230
	v_div_scale_f32 v226, vcc, v116, v120, v116
	v_mul_f32_e32 v227, v226, v225
	v_fma_f32 v228, -v224, v227, v226
	v_fmac_f32_e32 v227, v228, v225
	v_fma_f32 v224, -v224, v227, v226
	v_div_fmas_f32 v224, v224, v225, v227
	v_div_fixup_f32 v116, v224, v120, v116
	v_div_scale_f32 v231, vcc, v117, v121, v117
	v_mul_f32_e32 v232, v231, v230
	v_fma_f32 v233, -v229, v232, v231
	v_fmac_f32_e32 v232, v233, v230
	v_fma_f32 v229, -v229, v232, v231
	v_div_fmas_f32 v229, v229, v230, v232
	v_div_fixup_f32 v117, v229, v121, v117
	v_mul_f32_e32 v122, 0xbfb8aa3b, v122
	v_mul_f32_e32 v123, 0xbfb8aa3b, v123
	v_exp_f32_e32 v122, v122
	v_exp_f32_e32 v123, v123
	v_add_f32_e32 v122, 1.0, v122
	v_add_f32_e32 v123, 1.0, v123
	v_div_scale_f32 v224, s[26:27], v122, v122, v118
	v_div_scale_f32 v229, s[26:27], v123, v123, v119
	v_rcp_f32_e32 v225, v224
	v_rcp_f32_e32 v230, v229
	v_fma_f32 v226, -v224, v225, 1.0
	v_fma_f32 v231, -v229, v230, 1.0
	v_fmac_f32_e32 v225, v226, v225
	v_fmac_f32_e32 v230, v231, v230
	v_div_scale_f32 v226, vcc, v118, v122, v118
	v_mul_f32_e32 v227, v226, v225
	v_fma_f32 v228, -v224, v227, v226
	v_fmac_f32_e32 v227, v228, v225
	v_fma_f32 v224, -v224, v227, v226
	v_div_fmas_f32 v224, v224, v225, v227
	v_div_fixup_f32 v118, v224, v122, v118
	v_div_scale_f32 v231, vcc, v119, v123, v119
	v_mul_f32_e32 v232, v231, v230
	v_fma_f32 v233, -v229, v232, v231
	v_fmac_f32_e32 v232, v233, v230
	v_fma_f32 v229, -v229, v232, v231
	v_div_fmas_f32 v229, v229, v230, v232
	v_div_fixup_f32 v119, v229, v123, v119
	v_mul_f32_e32 v52, 0xbfb8aa3b, v52
	v_mul_f32_e32 v53, 0xbfb8aa3b, v53
	v_exp_f32_e32 v52, v52
	v_exp_f32_e32 v53, v53
	v_add_f32_e32 v52, 1.0, v52
	v_add_f32_e32 v53, 1.0, v53
	v_div_scale_f32 v224, s[26:27], v52, v52, v48
	v_div_scale_f32 v229, s[26:27], v53, v53, v49
	v_rcp_f32_e32 v225, v224
	v_rcp_f32_e32 v230, v229
	v_fma_f32 v226, -v224, v225, 1.0
	v_fma_f32 v231, -v229, v230, 1.0
	v_fmac_f32_e32 v225, v226, v225
	v_fmac_f32_e32 v230, v231, v230
	v_div_scale_f32 v226, vcc, v48, v52, v48
	v_mul_f32_e32 v227, v226, v225
	v_fma_f32 v228, -v224, v227, v226
	v_fmac_f32_e32 v227, v228, v225
	v_fma_f32 v224, -v224, v227, v226
	v_div_fmas_f32 v224, v224, v225, v227
	v_div_fixup_f32 v48, v224, v52, v48
	v_div_scale_f32 v231, vcc, v49, v53, v49
	v_mul_f32_e32 v232, v231, v230
	v_fma_f32 v233, -v229, v232, v231
	v_fmac_f32_e32 v232, v233, v230
	v_fma_f32 v229, -v229, v232, v231
	v_div_fmas_f32 v229, v229, v230, v232
	v_div_fixup_f32 v49, v229, v53, v49
	v_mul_f32_e32 v54, 0xbfb8aa3b, v54
	v_mul_f32_e32 v55, 0xbfb8aa3b, v55
	v_exp_f32_e32 v54, v54
	v_exp_f32_e32 v55, v55
	v_add_f32_e32 v54, 1.0, v54
	v_add_f32_e32 v55, 1.0, v55
	v_div_scale_f32 v224, s[26:27], v54, v54, v50
	v_div_scale_f32 v229, s[26:27], v55, v55, v51
	v_rcp_f32_e32 v225, v224
	v_rcp_f32_e32 v230, v229
	v_fma_f32 v226, -v224, v225, 1.0
	v_fma_f32 v231, -v229, v230, 1.0
	v_fmac_f32_e32 v225, v226, v225
	v_fmac_f32_e32 v230, v231, v230
	v_div_scale_f32 v226, vcc, v50, v54, v50
	v_mul_f32_e32 v227, v226, v225
	v_fma_f32 v228, -v224, v227, v226
	v_fmac_f32_e32 v227, v228, v225
	v_fma_f32 v224, -v224, v227, v226
	v_div_fmas_f32 v224, v224, v225, v227
	v_div_fixup_f32 v50, v224, v54, v50
	v_div_scale_f32 v231, vcc, v51, v55, v51
	v_mul_f32_e32 v232, v231, v230
	v_fma_f32 v233, -v229, v232, v231
	v_fmac_f32_e32 v232, v233, v230
	v_fma_f32 v229, -v229, v232, v231
	v_div_fmas_f32 v229, v229, v230, v232
	v_div_fixup_f32 v51, v229, v55, v51
	v_mul_f32_e32 v112, 0xbfb8aa3b, v112
	v_mul_f32_e32 v113, 0xbfb8aa3b, v113
	v_exp_f32_e32 v112, v112
	v_exp_f32_e32 v113, v113
	v_add_f32_e32 v112, 1.0, v112
	v_add_f32_e32 v113, 1.0, v113
	v_div_scale_f32 v224, s[26:27], v112, v112, v108
	v_div_scale_f32 v229, s[26:27], v113, v113, v109
	v_rcp_f32_e32 v225, v224
	v_rcp_f32_e32 v230, v229
	v_fma_f32 v226, -v224, v225, 1.0
	v_fma_f32 v231, -v229, v230, 1.0
	v_fmac_f32_e32 v225, v226, v225
	v_fmac_f32_e32 v230, v231, v230
	v_div_scale_f32 v226, vcc, v108, v112, v108
	v_mul_f32_e32 v227, v226, v225
	v_fma_f32 v228, -v224, v227, v226
	v_fmac_f32_e32 v227, v228, v225
	v_fma_f32 v224, -v224, v227, v226
	v_div_fmas_f32 v224, v224, v225, v227
	v_div_fixup_f32 v108, v224, v112, v108
	v_div_scale_f32 v231, vcc, v109, v113, v109
	v_mul_f32_e32 v232, v231, v230
	v_fma_f32 v233, -v229, v232, v231
	v_fmac_f32_e32 v232, v233, v230
	v_fma_f32 v229, -v229, v232, v231
	v_div_fmas_f32 v229, v229, v230, v232
	v_div_fixup_f32 v109, v229, v113, v109
	v_mul_f32_e32 v114, 0xbfb8aa3b, v114
	v_mul_f32_e32 v115, 0xbfb8aa3b, v115
	v_exp_f32_e32 v114, v114
	v_exp_f32_e32 v115, v115
	v_add_f32_e32 v114, 1.0, v114
	v_add_f32_e32 v115, 1.0, v115
	v_div_scale_f32 v224, s[26:27], v114, v114, v110
	v_div_scale_f32 v229, s[26:27], v115, v115, v111
	v_rcp_f32_e32 v225, v224
	v_rcp_f32_e32 v230, v229
	v_fma_f32 v226, -v224, v225, 1.0
	v_fma_f32 v231, -v229, v230, 1.0
	v_fmac_f32_e32 v225, v226, v225
	v_fmac_f32_e32 v230, v231, v230
	v_div_scale_f32 v226, vcc, v110, v114, v110
	v_mul_f32_e32 v227, v226, v225
	v_fma_f32 v228, -v224, v227, v226
	v_fmac_f32_e32 v227, v228, v225
;     DI void operator()(const f32x4 (&acc)[2][2][4][2], const Unit& u, int wr, int wc, int fr, int fq) const {
;     ...
;                 for (int m = 0; m < 4; ++m) { const size_t off = (size_t)(rbase + ai * HALF + m * 16) * D + col;
;                     const f32x4 x0 = *(const f32x4*)(src + off); const f32x4 za = acc[ai][bj][m][0], zb = acc[ai][bj][m][1]; f32x4 o;
; #pragma unroll
;                     for (int q = 0; q < 4; ++q) o[q] = za[q] / (1.f + __expf(-zb[q]));
;                     *(f32x4*)(dst + off) = x0 + g0 * o; }
	v_fma_f32 v224, -v224, v227, v226
	v_div_fmas_f32 v224, v224, v225, v227
	v_div_fixup_f32 v110, v224, v114, v110
	v_div_scale_f32 v231, vcc, v111, v115, v111
	v_mul_f32_e32 v232, v231, v230
	v_fma_f32 v233, -v229, v232, v231
	v_fmac_f32_e32 v232, v233, v230
	v_fma_f32 v229, -v229, v232, v231
	v_div_fmas_f32 v229, v229, v230, v232
	v_div_fixup_f32 v111, v229, v115, v111
	v_mul_f32_e32 v44, 0xbfb8aa3b, v44
	v_mul_f32_e32 v45, 0xbfb8aa3b, v45
	v_exp_f32_e32 v44, v44
	v_exp_f32_e32 v45, v45
	v_add_f32_e32 v44, 1.0, v44
	v_add_f32_e32 v45, 1.0, v45
	v_div_scale_f32 v224, s[26:27], v44, v44, v40
	v_div_scale_f32 v229, s[26:27], v45, v45, v41
	v_rcp_f32_e32 v225, v224
	v_rcp_f32_e32 v230, v229
	v_fma_f32 v226, -v224, v225, 1.0
	v_fma_f32 v231, -v229, v230, 1.0
	v_fmac_f32_e32 v225, v226, v225
	v_fmac_f32_e32 v230, v231, v230
	v_div_scale_f32 v226, vcc, v40, v44, v40
	v_mul_f32_e32 v227, v226, v225
	v_fma_f32 v228, -v224, v227, v226
	v_fmac_f32_e32 v227, v228, v225
	v_fma_f32 v224, -v224, v227, v226
	v_div_fmas_f32 v224, v224, v225, v227
	v_div_fixup_f32 v40, v224, v44, v40
	v_div_scale_f32 v231, vcc, v41, v45, v41
	v_mul_f32_e32 v232, v231, v230
	v_fma_f32 v233, -v229, v232, v231
	v_fmac_f32_e32 v232, v233, v230
	v_fma_f32 v229, -v229, v232, v231
	v_div_fmas_f32 v229, v229, v230, v232
	v_div_fixup_f32 v41, v229, v45, v41
	v_mul_f32_e32 v46, 0xbfb8aa3b, v46
	v_mul_f32_e32 v47, 0xbfb8aa3b, v47
	v_exp_f32_e32 v46, v46
	v_exp_f32_e32 v47, v47
	v_add_f32_e32 v46, 1.0, v46
	v_add_f32_e32 v47, 1.0, v47
	v_div_scale_f32 v224, s[26:27], v46, v46, v42
	v_div_scale_f32 v229, s[26:27], v47, v47, v43
	v_rcp_f32_e32 v225, v224
	v_rcp_f32_e32 v230, v229
	v_fma_f32 v226, -v224, v225, 1.0
	v_fma_f32 v231, -v229, v230, 1.0
	v_fmac_f32_e32 v225, v226, v225
	v_fmac_f32_e32 v230, v231, v230
	v_div_scale_f32 v226, vcc, v42, v46, v42
	v_mul_f32_e32 v227, v226, v225
	v_fma_f32 v228, -v224, v227, v226
	v_fmac_f32_e32 v227, v228, v225
	v_fma_f32 v224, -v224, v227, v226
	v_div_fmas_f32 v224, v224, v225, v227
	v_div_fixup_f32 v42, v224, v46, v42
	v_div_scale_f32 v231, vcc, v43, v47, v43
	v_mul_f32_e32 v232, v231, v230
	v_fma_f32 v233, -v229, v232, v231
	v_fmac_f32_e32 v232, v233, v230
	v_fma_f32 v229, -v229, v232, v231
	v_div_fmas_f32 v229, v229, v230, v232
	v_div_fixup_f32 v43, v229, v47, v43
	v_mul_f32_e32 v104, 0xbfb8aa3b, v104
	v_mul_f32_e32 v105, 0xbfb8aa3b, v105
	v_exp_f32_e32 v104, v104
	v_exp_f32_e32 v105, v105
	v_add_f32_e32 v104, 1.0, v104
	v_add_f32_e32 v105, 1.0, v105
	v_div_scale_f32 v224, s[26:27], v104, v104, v100
	v_div_scale_f32 v229, s[26:27], v105, v105, v101
	v_rcp_f32_e32 v225, v224
	v_rcp_f32_e32 v230, v229
	v_fma_f32 v226, -v224, v225, 1.0
	v_fma_f32 v231, -v229, v230, 1.0
	v_fmac_f32_e32 v225, v226, v225
	v_fmac_f32_e32 v230, v231, v230
	v_div_scale_f32 v226, vcc, v100, v104, v100
	v_mul_f32_e32 v227, v226, v225
	v_fma_f32 v228, -v224, v227, v226
	v_fmac_f32_e32 v227, v228, v225
	v_fma_f32 v224, -v224, v227, v226
	v_div_fmas_f32 v224, v224, v225, v227
	v_div_fixup_f32 v100, v224, v104, v100
	v_div_scale_f32 v231, vcc, v101, v105, v101
	v_mul_f32_e32 v232, v231, v230
	v_fma_f32 v233, -v229, v232, v231
	v_fmac_f32_e32 v232, v233, v230
	v_fma_f32 v229, -v229, v232, v231
	v_div_fmas_f32 v229, v229, v230, v232
	v_div_fixup_f32 v101, v229, v105, v101
	v_mul_f32_e32 v106, 0xbfb8aa3b, v106
	v_mul_f32_e32 v107, 0xbfb8aa3b, v107
	v_exp_f32_e32 v106, v106
	v_exp_f32_e32 v107, v107
	v_add_f32_e32 v106, 1.0, v106
	v_add_f32_e32 v107, 1.0, v107
	v_div_scale_f32 v224, s[26:27], v106, v106, v102
	v_div_scale_f32 v229, s[26:27], v107, v107, v103
	v_rcp_f32_e32 v225, v224
	v_rcp_f32_e32 v230, v229
	v_fma_f32 v226, -v224, v225, 1.0
	v_fma_f32 v231, -v229, v230, 1.0
	v_fmac_f32_e32 v225, v226, v225
	v_fmac_f32_e32 v230, v231, v230
	v_div_scale_f32 v226, vcc, v102, v106, v102
	v_mul_f32_e32 v227, v226, v225
	v_fma_f32 v228, -v224, v227, v226
	v_fmac_f32_e32 v227, v228, v225
	v_fma_f32 v224, -v224, v227, v226
	v_div_fmas_f32 v224, v224, v225, v227
	v_div_fixup_f32 v102, v224, v106, v102
	v_div_scale_f32 v231, vcc, v103, v107, v103
	v_mul_f32_e32 v232, v231, v230
	v_fma_f32 v233, -v229, v232, v231
	v_fmac_f32_e32 v232, v233, v230
	v_fma_f32 v229, -v229, v232, v231
	v_div_fmas_f32 v229, v229, v230, v232
	v_div_fixup_f32 v103, v229, v107, v103
	v_mul_f32_e32 v36, 0xbfb8aa3b, v36
	v_mul_f32_e32 v37, 0xbfb8aa3b, v37
	v_exp_f32_e32 v36, v36
	v_exp_f32_e32 v37, v37
	v_add_f32_e32 v36, 1.0, v36
	v_add_f32_e32 v37, 1.0, v37
	v_div_scale_f32 v224, s[26:27], v36, v36, v32
	v_div_scale_f32 v229, s[26:27], v37, v37, v33
	v_rcp_f32_e32 v225, v224
	v_rcp_f32_e32 v230, v229
	v_fma_f32 v226, -v224, v225, 1.0
	v_fma_f32 v231, -v229, v230, 1.0
	v_fmac_f32_e32 v225, v226, v225
	v_fmac_f32_e32 v230, v231, v230
	v_div_scale_f32 v226, vcc, v32, v36, v32
	v_mul_f32_e32 v227, v226, v225
	v_fma_f32 v228, -v224, v227, v226
	v_fmac_f32_e32 v227, v228, v225
	v_fma_f32 v224, -v224, v227, v226
	v_div_fmas_f32 v224, v224, v225, v227
	v_div_fixup_f32 v32, v224, v36, v32
	v_div_scale_f32 v231, vcc, v33, v37, v33
	v_mul_f32_e32 v232, v231, v230
	v_fma_f32 v233, -v229, v232, v231
	v_fmac_f32_e32 v232, v233, v230
	v_fma_f32 v229, -v229, v232, v231
	v_div_fmas_f32 v229, v229, v230, v232
	v_div_fixup_f32 v33, v229, v37, v33
	v_mul_f32_e32 v38, 0xbfb8aa3b, v38
	v_mul_f32_e32 v39, 0xbfb8aa3b, v39
	v_exp_f32_e32 v38, v38
	v_exp_f32_e32 v39, v39
	v_add_f32_e32 v38, 1.0, v38
	v_add_f32_e32 v39, 1.0, v39
	v_div_scale_f32 v224, s[26:27], v38, v38, v34
	v_div_scale_f32 v229, s[26:27], v39, v39, v35
	v_rcp_f32_e32 v225, v224
	v_rcp_f32_e32 v230, v229
	v_fma_f32 v226, -v224, v225, 1.0
	v_fma_f32 v231, -v229, v230, 1.0
;     DI void operator()(const f32x4 (&acc)[2][2][4][2], const Unit& u, int wr, int wc, int fr, int fq) const {
;     ...
;                 for (int m = 0; m < 4; ++m) { const size_t off = (size_t)(rbase + ai * HALF + m * 16) * D + col;
;                     const f32x4 x0 = *(const f32x4*)(src + off); const f32x4 za = acc[ai][bj][m][0], zb = acc[ai][bj][m][1]; f32x4 o;
; #pragma unroll
;                     for (int q = 0; q < 4; ++q) o[q] = za[q] / (1.f + __expf(-zb[q]));
;                     *(f32x4*)(dst + off) = x0 + g0 * o; }
	v_fmac_f32_e32 v225, v226, v225
	v_fmac_f32_e32 v230, v231, v230
	v_div_scale_f32 v226, vcc, v34, v38, v34
	v_mul_f32_e32 v227, v226, v225
	v_fma_f32 v228, -v224, v227, v226
	v_fmac_f32_e32 v227, v228, v225
	v_fma_f32 v224, -v224, v227, v226
	v_div_fmas_f32 v224, v224, v225, v227
	v_div_fixup_f32 v34, v224, v38, v34
	v_div_scale_f32 v231, vcc, v35, v39, v35
	v_mul_f32_e32 v232, v231, v230
	v_fma_f32 v233, -v229, v232, v231
	v_fmac_f32_e32 v232, v233, v230
	v_fma_f32 v229, -v229, v232, v231
	v_div_fmas_f32 v229, v229, v230, v232
	v_div_fixup_f32 v35, v229, v39, v35
	global_load_dwordx4 v[128:131], v[152:153], off
	global_load_dwordx4 v[60:63], v[152:153], off offset:256
	v_lshl_add_u64 v[152:153], v[152:153], 0, s[12:13]
	global_load_dwordx4 v[120:123], v[152:153], off
	global_load_dwordx4 v[52:55], v[152:153], off offset:256
	v_lshl_add_u64 v[152:153], v[152:153], 0, s[12:13]
	global_load_dwordx4 v[112:115], v[152:153], off
	global_load_dwordx4 v[44:47], v[152:153], off offset:256
	v_lshl_add_u64 v[152:153], v[152:153], 0, s[12:13]
	global_load_dwordx4 v[104:107], v[152:153], off
	global_load_dwordx4 v[36:39], v[152:153], off offset:256
	v_mul_f32_e32 v96, 0xbfb8aa3b, v96
	v_mul_f32_e32 v97, 0xbfb8aa3b, v97
	v_exp_f32_e32 v96, v96
	v_exp_f32_e32 v97, v97
	v_add_f32_e32 v96, 1.0, v96
	v_add_f32_e32 v97, 1.0, v97
	v_div_scale_f32 v224, s[26:27], v96, v96, v92
	v_div_scale_f32 v229, s[26:27], v97, v97, v93
	v_rcp_f32_e32 v225, v224
	v_rcp_f32_e32 v230, v229
	v_fma_f32 v226, -v224, v225, 1.0
	v_fma_f32 v231, -v229, v230, 1.0
	v_fmac_f32_e32 v225, v226, v225
	v_fmac_f32_e32 v230, v231, v230
	v_div_scale_f32 v226, vcc, v92, v96, v92
	v_mul_f32_e32 v227, v226, v225
	v_fma_f32 v228, -v224, v227, v226
	v_fmac_f32_e32 v227, v228, v225
	v_fma_f32 v224, -v224, v227, v226
	v_div_fmas_f32 v224, v224, v225, v227
	v_div_fixup_f32 v92, v224, v96, v92
	v_div_scale_f32 v231, vcc, v93, v97, v93
	v_mul_f32_e32 v232, v231, v230
	v_fma_f32 v233, -v229, v232, v231
	v_fmac_f32_e32 v232, v233, v230
	v_fma_f32 v229, -v229, v232, v231
	v_div_fmas_f32 v229, v229, v230, v232
	v_div_fixup_f32 v93, v229, v97, v93
	v_mul_f32_e32 v98, 0xbfb8aa3b, v98
	v_mul_f32_e32 v99, 0xbfb8aa3b, v99
	v_exp_f32_e32 v98, v98
	v_exp_f32_e32 v99, v99
	v_add_f32_e32 v98, 1.0, v98
	v_add_f32_e32 v99, 1.0, v99
	v_div_scale_f32 v224, s[26:27], v98, v98, v94
	v_div_scale_f32 v229, s[26:27], v99, v99, v95
	v_rcp_f32_e32 v225, v224
	v_rcp_f32_e32 v230, v229
	v_fma_f32 v226, -v224, v225, 1.0
	v_fma_f32 v231, -v229, v230, 1.0
	v_fmac_f32_e32 v225, v226, v225
	v_fmac_f32_e32 v230, v231, v230
	v_div_scale_f32 v226, vcc, v94, v98, v94
	v_mul_f32_e32 v227, v226, v225
	v_fma_f32 v228, -v224, v227, v226
	v_fmac_f32_e32 v227, v228, v225
	v_fma_f32 v224, -v224, v227, v226
	v_div_fmas_f32 v224, v224, v225, v227
	v_div_fixup_f32 v94, v224, v98, v94
	v_div_scale_f32 v231, vcc, v95, v99, v95
	v_mul_f32_e32 v232, v231, v230
	v_fma_f32 v233, -v229, v232, v231
	v_fmac_f32_e32 v232, v233, v230
	v_fma_f32 v229, -v229, v232, v231
	v_div_fmas_f32 v229, v229, v230, v232
	v_div_fixup_f32 v95, v229, v99, v95
	v_mul_f32_e32 v28, 0xbfb8aa3b, v28
	v_mul_f32_e32 v29, 0xbfb8aa3b, v29
	v_exp_f32_e32 v28, v28
	v_exp_f32_e32 v29, v29
	v_add_f32_e32 v28, 1.0, v28
	v_add_f32_e32 v29, 1.0, v29
	v_div_scale_f32 v224, s[26:27], v28, v28, v24
	v_div_scale_f32 v229, s[26:27], v29, v29, v25
	v_rcp_f32_e32 v225, v224
	v_rcp_f32_e32 v230, v229
	v_fma_f32 v226, -v224, v225, 1.0
	v_fma_f32 v231, -v229, v230, 1.0
	v_fmac_f32_e32 v225, v226, v225
	v_fmac_f32_e32 v230, v231, v230
	v_div_scale_f32 v226, vcc, v24, v28, v24
	v_mul_f32_e32 v227, v226, v225
	v_fma_f32 v228, -v224, v227, v226
	v_fmac_f32_e32 v227, v228, v225
	v_fma_f32 v224, -v224, v227, v226
	v_div_fmas_f32 v224, v224, v225, v227
	v_div_fixup_f32 v24, v224, v28, v24
	v_div_scale_f32 v231, vcc, v25, v29, v25
	v_mul_f32_e32 v232, v231, v230
	v_fma_f32 v233, -v229, v232, v231
	v_fmac_f32_e32 v232, v233, v230
	v_fma_f32 v229, -v229, v232, v231
	v_div_fmas_f32 v229, v229, v230, v232
	v_div_fixup_f32 v25, v229, v29, v25
	v_mul_f32_e32 v30, 0xbfb8aa3b, v30
	v_mul_f32_e32 v31, 0xbfb8aa3b, v31
	v_exp_f32_e32 v30, v30
	v_exp_f32_e32 v31, v31
	v_add_f32_e32 v30, 1.0, v30
	v_add_f32_e32 v31, 1.0, v31
	v_div_scale_f32 v224, s[26:27], v30, v30, v26
	v_div_scale_f32 v229, s[26:27], v31, v31, v27
	v_rcp_f32_e32 v225, v224
	v_rcp_f32_e32 v230, v229
	v_fma_f32 v226, -v224, v225, 1.0
	v_fma_f32 v231, -v229, v230, 1.0
	v_fmac_f32_e32 v225, v226, v225
	v_fmac_f32_e32 v230, v231, v230
	v_div_scale_f32 v226, vcc, v26, v30, v26
	v_mul_f32_e32 v227, v226, v225
	v_fma_f32 v228, -v224, v227, v226
	v_fmac_f32_e32 v227, v228, v225
	v_fma_f32 v224, -v224, v227, v226
	v_div_fmas_f32 v224, v224, v225, v227
	v_div_fixup_f32 v26, v224, v30, v26
	v_div_scale_f32 v231, vcc, v27, v31, v27
	v_mul_f32_e32 v232, v231, v230
	v_fma_f32 v233, -v229, v232, v231
	v_fmac_f32_e32 v232, v233, v230
	v_fma_f32 v229, -v229, v232, v231
	v_div_fmas_f32 v229, v229, v230, v232
	v_div_fixup_f32 v27, v229, v31, v27
	v_mul_f32_e32 v88, 0xbfb8aa3b, v88
	v_mul_f32_e32 v89, 0xbfb8aa3b, v89
	v_exp_f32_e32 v88, v88
	v_exp_f32_e32 v89, v89
	v_add_f32_e32 v88, 1.0, v88
	v_add_f32_e32 v89, 1.0, v89
	v_div_scale_f32 v224, s[26:27], v88, v88, v80
	v_div_scale_f32 v229, s[26:27], v89, v89, v81
	v_rcp_f32_e32 v225, v224
	v_rcp_f32_e32 v230, v229
	v_fma_f32 v226, -v224, v225, 1.0
	v_fma_f32 v231, -v229, v230, 1.0
	v_fmac_f32_e32 v225, v226, v225
	v_fmac_f32_e32 v230, v231, v230
	v_div_scale_f32 v226, vcc, v80, v88, v80
	v_mul_f32_e32 v227, v226, v225
	v_fma_f32 v228, -v224, v227, v226
	v_fmac_f32_e32 v227, v228, v225
	v_fma_f32 v224, -v224, v227, v226
;     DI void operator()(const f32x4 (&acc)[2][2][4][2], const Unit& u, int wr, int wc, int fr, int fq) const {
;     ...
;                 for (int m = 0; m < 4; ++m) { const size_t off = (size_t)(rbase + ai * HALF + m * 16) * D + col;
;                     const f32x4 x0 = *(const f32x4*)(src + off); const f32x4 za = acc[ai][bj][m][0], zb = acc[ai][bj][m][1]; f32x4 o;
; #pragma unroll
;                     for (int q = 0; q < 4; ++q) o[q] = za[q] / (1.f + __expf(-zb[q]));
;                     *(f32x4*)(dst + off) = x0 + g0 * o; }
	v_div_fmas_f32 v224, v224, v225, v227
	v_div_fixup_f32 v80, v224, v88, v80
	v_div_scale_f32 v231, vcc, v81, v89, v81
	v_mul_f32_e32 v232, v231, v230
	v_fma_f32 v233, -v229, v232, v231
	v_fmac_f32_e32 v232, v233, v230
	v_fma_f32 v229, -v229, v232, v231
	v_div_fmas_f32 v229, v229, v230, v232
	v_div_fixup_f32 v81, v229, v89, v81
	v_mul_f32_e32 v90, 0xbfb8aa3b, v90
	v_mul_f32_e32 v91, 0xbfb8aa3b, v91
	v_exp_f32_e32 v90, v90
	v_exp_f32_e32 v91, v91
	v_add_f32_e32 v90, 1.0, v90
	v_add_f32_e32 v91, 1.0, v91
	v_div_scale_f32 v224, s[26:27], v90, v90, v82
	v_div_scale_f32 v229, s[26:27], v91, v91, v83
	v_rcp_f32_e32 v225, v224
	v_rcp_f32_e32 v230, v229
	v_fma_f32 v226, -v224, v225, 1.0
	v_fma_f32 v231, -v229, v230, 1.0
	v_fmac_f32_e32 v225, v226, v225
	v_fmac_f32_e32 v230, v231, v230
	v_div_scale_f32 v226, vcc, v82, v90, v82
	v_mul_f32_e32 v227, v226, v225
	v_fma_f32 v228, -v224, v227, v226
	v_fmac_f32_e32 v227, v228, v225
	v_fma_f32 v224, -v224, v227, v226
	v_div_fmas_f32 v224, v224, v225, v227
	v_div_fixup_f32 v82, v224, v90, v82
	v_div_scale_f32 v231, vcc, v83, v91, v83
	v_mul_f32_e32 v232, v231, v230
	v_fma_f32 v233, -v229, v232, v231
	v_fmac_f32_e32 v232, v233, v230
	v_fma_f32 v229, -v229, v232, v231
	v_div_fmas_f32 v229, v229, v230, v232
	v_div_fixup_f32 v83, v229, v91, v83
	v_mul_f32_e32 v20, 0xbfb8aa3b, v20
	v_mul_f32_e32 v21, 0xbfb8aa3b, v21
	v_exp_f32_e32 v20, v20
	v_exp_f32_e32 v21, v21
	v_add_f32_e32 v20, 1.0, v20
	v_add_f32_e32 v21, 1.0, v21
	v_div_scale_f32 v224, s[26:27], v20, v20, v16
	v_div_scale_f32 v229, s[26:27], v21, v21, v17
	v_rcp_f32_e32 v225, v224
	v_rcp_f32_e32 v230, v229
	v_fma_f32 v226, -v224, v225, 1.0
	v_fma_f32 v231, -v229, v230, 1.0
	v_fmac_f32_e32 v225, v226, v225
	v_fmac_f32_e32 v230, v231, v230
	v_div_scale_f32 v226, vcc, v16, v20, v16
	v_mul_f32_e32 v227, v226, v225
	v_fma_f32 v228, -v224, v227, v226
	v_fmac_f32_e32 v227, v228, v225
	v_fma_f32 v224, -v224, v227, v226
	v_div_fmas_f32 v224, v224, v225, v227
	v_div_fixup_f32 v16, v224, v20, v16
	v_div_scale_f32 v231, vcc, v17, v21, v17
	v_mul_f32_e32 v232, v231, v230
	v_fma_f32 v233, -v229, v232, v231
	v_fmac_f32_e32 v232, v233, v230
	v_fma_f32 v229, -v229, v232, v231
	v_div_fmas_f32 v229, v229, v230, v232
	v_div_fixup_f32 v17, v229, v21, v17
	v_mul_f32_e32 v22, 0xbfb8aa3b, v22
	v_mul_f32_e32 v23, 0xbfb8aa3b, v23
	v_exp_f32_e32 v22, v22
	v_exp_f32_e32 v23, v23
	v_add_f32_e32 v22, 1.0, v22
	v_add_f32_e32 v23, 1.0, v23
	v_div_scale_f32 v224, s[26:27], v22, v22, v18
	v_div_scale_f32 v229, s[26:27], v23, v23, v19
	v_rcp_f32_e32 v225, v224
	v_rcp_f32_e32 v230, v229
	v_fma_f32 v226, -v224, v225, 1.0
	v_fma_f32 v231, -v229, v230, 1.0
	v_fmac_f32_e32 v225, v226, v225
	v_fmac_f32_e32 v230, v231, v230
	v_div_scale_f32 v226, vcc, v18, v22, v18
	v_mul_f32_e32 v227, v226, v225
	v_fma_f32 v228, -v224, v227, v226
	v_fmac_f32_e32 v227, v228, v225
	v_fma_f32 v224, -v224, v227, v226
	v_div_fmas_f32 v224, v224, v225, v227
	v_div_fixup_f32 v18, v224, v22, v18
	v_div_scale_f32 v231, vcc, v19, v23, v19
	v_mul_f32_e32 v232, v231, v230
	v_fma_f32 v233, -v229, v232, v231
	v_fmac_f32_e32 v232, v233, v230
	v_fma_f32 v229, -v229, v232, v231
	v_div_fmas_f32 v229, v229, v230, v232
	v_div_fixup_f32 v19, v229, v23, v19
	v_mul_f32_e32 v76, 0xbfb8aa3b, v76
	v_mul_f32_e32 v77, 0xbfb8aa3b, v77
	v_exp_f32_e32 v76, v76
	v_exp_f32_e32 v77, v77
	v_add_f32_e32 v76, 1.0, v76
	v_add_f32_e32 v77, 1.0, v77
	v_div_scale_f32 v224, s[26:27], v76, v76, v72
	v_div_scale_f32 v229, s[26:27], v77, v77, v73
	v_rcp_f32_e32 v225, v224
	v_rcp_f32_e32 v230, v229
	v_fma_f32 v226, -v224, v225, 1.0
	v_fma_f32 v231, -v229, v230, 1.0
	v_fmac_f32_e32 v225, v226, v225
	v_fmac_f32_e32 v230, v231, v230
	v_div_scale_f32 v226, vcc, v72, v76, v72
	v_mul_f32_e32 v227, v226, v225
	v_fma_f32 v228, -v224, v227, v226
	v_fmac_f32_e32 v227, v228, v225
	v_fma_f32 v224, -v224, v227, v226
	v_div_fmas_f32 v224, v224, v225, v227
	v_div_fixup_f32 v72, v224, v76, v72
	v_div_scale_f32 v231, vcc, v73, v77, v73
	v_mul_f32_e32 v232, v231, v230
	v_fma_f32 v233, -v229, v232, v231
	v_fmac_f32_e32 v232, v233, v230
	v_fma_f32 v229, -v229, v232, v231
	v_div_fmas_f32 v229, v229, v230, v232
	v_div_fixup_f32 v73, v229, v77, v73
	v_mul_f32_e32 v78, 0xbfb8aa3b, v78
	v_mul_f32_e32 v79, 0xbfb8aa3b, v79
	v_exp_f32_e32 v78, v78
	v_exp_f32_e32 v79, v79
	v_add_f32_e32 v78, 1.0, v78
	v_add_f32_e32 v79, 1.0, v79
	v_div_scale_f32 v224, s[26:27], v78, v78, v74
	v_div_scale_f32 v229, s[26:27], v79, v79, v75
	v_rcp_f32_e32 v225, v224
	v_rcp_f32_e32 v230, v229
	v_fma_f32 v226, -v224, v225, 1.0
	v_fma_f32 v231, -v229, v230, 1.0
	v_fmac_f32_e32 v225, v226, v225
	v_fmac_f32_e32 v230, v231, v230
	v_div_scale_f32 v226, vcc, v74, v78, v74
	v_mul_f32_e32 v227, v226, v225
	v_fma_f32 v228, -v224, v227, v226
	v_fmac_f32_e32 v227, v228, v225
	v_fma_f32 v224, -v224, v227, v226
	v_div_fmas_f32 v224, v224, v225, v227
	v_div_fixup_f32 v74, v224, v78, v74
	v_div_scale_f32 v231, vcc, v75, v79, v75
	v_mul_f32_e32 v232, v231, v230
	v_fma_f32 v233, -v229, v232, v231
	v_fmac_f32_e32 v232, v233, v230
	v_fma_f32 v229, -v229, v232, v231
	v_div_fmas_f32 v229, v229, v230, v232
	v_div_fixup_f32 v75, v229, v79, v75
	v_mul_f32_e32 v12, 0xbfb8aa3b, v12
	v_mul_f32_e32 v13, 0xbfb8aa3b, v13
	v_exp_f32_e32 v12, v12
	v_exp_f32_e32 v13, v13
	v_add_f32_e32 v12, 1.0, v12
	v_add_f32_e32 v13, 1.0, v13
	v_div_scale_f32 v224, s[26:27], v12, v12, v8
	v_div_scale_f32 v229, s[26:27], v13, v13, v9
	v_rcp_f32_e32 v225, v224
	v_rcp_f32_e32 v230, v229
	v_fma_f32 v226, -v224, v225, 1.0
	v_fma_f32 v231, -v229, v230, 1.0
	v_fmac_f32_e32 v225, v226, v225
	v_fmac_f32_e32 v230, v231, v230
	v_div_scale_f32 v226, vcc, v8, v12, v8
;     DI void operator()(const f32x4 (&acc)[2][2][4][2], const Unit& u, int wr, int wc, int fr, int fq) const {
;     ...
;                 for (int m = 0; m < 4; ++m) { const size_t off = (size_t)(rbase + ai * HALF + m * 16) * D + col;
;                     const f32x4 x0 = *(const f32x4*)(src + off); const f32x4 za = acc[ai][bj][m][0], zb = acc[ai][bj][m][1]; f32x4 o;
; #pragma unroll
;                     for (int q = 0; q < 4; ++q) o[q] = za[q] / (1.f + __expf(-zb[q]));
;                     *(f32x4*)(dst + off) = x0 + g0 * o; }
	v_mul_f32_e32 v227, v226, v225
	v_fma_f32 v228, -v224, v227, v226
	v_fmac_f32_e32 v227, v228, v225
	v_fma_f32 v224, -v224, v227, v226
	v_div_fmas_f32 v224, v224, v225, v227
	v_div_fixup_f32 v8, v224, v12, v8
	v_div_scale_f32 v231, vcc, v9, v13, v9
	v_mul_f32_e32 v232, v231, v230
	v_fma_f32 v233, -v229, v232, v231
	v_fmac_f32_e32 v232, v233, v230
	v_fma_f32 v229, -v229, v232, v231
	v_div_fmas_f32 v229, v229, v230, v232
	v_div_fixup_f32 v9, v229, v13, v9
	v_mul_f32_e32 v14, 0xbfb8aa3b, v14
	v_mul_f32_e32 v15, 0xbfb8aa3b, v15
	v_exp_f32_e32 v14, v14
	v_exp_f32_e32 v15, v15
	v_add_f32_e32 v14, 1.0, v14
	v_add_f32_e32 v15, 1.0, v15
	v_div_scale_f32 v224, s[26:27], v14, v14, v10
	v_div_scale_f32 v229, s[26:27], v15, v15, v11
	v_rcp_f32_e32 v225, v224
	v_rcp_f32_e32 v230, v229
	v_fma_f32 v226, -v224, v225, 1.0
	v_fma_f32 v231, -v229, v230, 1.0
	v_fmac_f32_e32 v225, v226, v225
	v_fmac_f32_e32 v230, v231, v230
	v_div_scale_f32 v226, vcc, v10, v14, v10
	v_mul_f32_e32 v227, v226, v225
	v_fma_f32 v228, -v224, v227, v226
	v_fmac_f32_e32 v227, v228, v225
	v_fma_f32 v224, -v224, v227, v226
	v_div_fmas_f32 v224, v224, v225, v227
	v_div_fixup_f32 v10, v224, v14, v10
	v_div_scale_f32 v231, vcc, v11, v15, v11
	v_mul_f32_e32 v232, v231, v230
	v_fma_f32 v233, -v229, v232, v231
	v_fmac_f32_e32 v232, v233, v230
	v_fma_f32 v229, -v229, v232, v231
	v_div_fmas_f32 v229, v229, v230, v232
	v_div_fixup_f32 v11, v229, v15, v11
	v_mul_f32_e32 v68, 0xbfb8aa3b, v68
	v_mul_f32_e32 v69, 0xbfb8aa3b, v69
	v_exp_f32_e32 v68, v68
	v_exp_f32_e32 v69, v69
	v_add_f32_e32 v68, 1.0, v68
	v_add_f32_e32 v69, 1.0, v69
	v_div_scale_f32 v224, s[26:27], v68, v68, v64
	v_div_scale_f32 v229, s[26:27], v69, v69, v65
	v_rcp_f32_e32 v225, v224
	v_rcp_f32_e32 v230, v229
	v_fma_f32 v226, -v224, v225, 1.0
	v_fma_f32 v231, -v229, v230, 1.0
	v_fmac_f32_e32 v225, v226, v225
	v_fmac_f32_e32 v230, v231, v230
	v_div_scale_f32 v226, vcc, v64, v68, v64
	v_mul_f32_e32 v227, v226, v225
	v_fma_f32 v228, -v224, v227, v226
	v_fmac_f32_e32 v227, v228, v225
	v_fma_f32 v224, -v224, v227, v226
	v_div_fmas_f32 v224, v224, v225, v227
	v_div_fixup_f32 v64, v224, v68, v64
	v_div_scale_f32 v231, vcc, v65, v69, v65
	v_mul_f32_e32 v232, v231, v230
	v_fma_f32 v233, -v229, v232, v231
	v_fmac_f32_e32 v232, v233, v230
	v_fma_f32 v229, -v229, v232, v231
	v_div_fmas_f32 v229, v229, v230, v232
	v_div_fixup_f32 v65, v229, v69, v65
	v_mul_f32_e32 v70, 0xbfb8aa3b, v70
	v_mul_f32_e32 v71, 0xbfb8aa3b, v71
	v_exp_f32_e32 v70, v70
	v_exp_f32_e32 v71, v71
	v_add_f32_e32 v70, 1.0, v70
	v_add_f32_e32 v71, 1.0, v71
	v_div_scale_f32 v224, s[26:27], v70, v70, v66
	v_div_scale_f32 v229, s[26:27], v71, v71, v67
	v_rcp_f32_e32 v225, v224
	v_rcp_f32_e32 v230, v229
	v_fma_f32 v226, -v224, v225, 1.0
	v_fma_f32 v231, -v229, v230, 1.0
	v_fmac_f32_e32 v225, v226, v225
	v_fmac_f32_e32 v230, v231, v230
	v_div_scale_f32 v226, vcc, v66, v70, v66
	v_mul_f32_e32 v227, v226, v225
	v_fma_f32 v228, -v224, v227, v226
	v_fmac_f32_e32 v227, v228, v225
	v_fma_f32 v224, -v224, v227, v226
	v_div_fmas_f32 v224, v224, v225, v227
	v_div_fixup_f32 v66, v224, v70, v66
	v_div_scale_f32 v231, vcc, v67, v71, v67
	v_mul_f32_e32 v232, v231, v230
	v_fma_f32 v233, -v229, v232, v231
	v_fmac_f32_e32 v232, v233, v230
	v_fma_f32 v229, -v229, v232, v231
	v_div_fmas_f32 v229, v229, v230, v232
	v_div_fixup_f32 v67, v229, v71, v67
	v_mul_f32_e32 v4, 0xbfb8aa3b, v4
	v_mul_f32_e32 v5, 0xbfb8aa3b, v5
	v_exp_f32_e32 v4, v4
	v_exp_f32_e32 v5, v5
	v_add_f32_e32 v4, 1.0, v4
	v_add_f32_e32 v5, 1.0, v5
	v_div_scale_f32 v224, s[26:27], v4, v4, v0
	v_div_scale_f32 v229, s[26:27], v5, v5, v1
	v_rcp_f32_e32 v225, v224
	v_rcp_f32_e32 v230, v229
	v_fma_f32 v226, -v224, v225, 1.0
	v_fma_f32 v231, -v229, v230, 1.0
	v_fmac_f32_e32 v225, v226, v225
	v_fmac_f32_e32 v230, v231, v230
	v_div_scale_f32 v226, vcc, v0, v4, v0
	v_mul_f32_e32 v227, v226, v225
	v_fma_f32 v228, -v224, v227, v226
	v_fmac_f32_e32 v227, v228, v225
	v_fma_f32 v224, -v224, v227, v226
	v_div_fmas_f32 v224, v224, v225, v227
	v_div_fixup_f32 v0, v224, v4, v0
	v_div_scale_f32 v231, vcc, v1, v5, v1
	v_mul_f32_e32 v232, v231, v230
	v_fma_f32 v233, -v229, v232, v231
	v_fmac_f32_e32 v232, v233, v230
	v_fma_f32 v229, -v229, v232, v231
	v_div_fmas_f32 v229, v229, v230, v232
	v_div_fixup_f32 v1, v229, v5, v1
	v_mul_f32_e32 v6, 0xbfb8aa3b, v6
	v_mul_f32_e32 v7, 0xbfb8aa3b, v7
	v_exp_f32_e32 v6, v6
	v_exp_f32_e32 v7, v7
	v_add_f32_e32 v6, 1.0, v6
	v_add_f32_e32 v7, 1.0, v7
	v_div_scale_f32 v224, s[26:27], v6, v6, v2
	v_div_scale_f32 v229, s[26:27], v7, v7, v3
	v_rcp_f32_e32 v225, v224
	v_rcp_f32_e32 v230, v229
	v_fma_f32 v226, -v224, v225, 1.0
	v_fma_f32 v231, -v229, v230, 1.0
	v_fmac_f32_e32 v225, v226, v225
	v_fmac_f32_e32 v230, v231, v230
	v_div_scale_f32 v226, vcc, v2, v6, v2
	v_mul_f32_e32 v227, v226, v225
	v_fma_f32 v228, -v224, v227, v226
	v_fmac_f32_e32 v227, v228, v225
	v_fma_f32 v224, -v224, v227, v226
	v_div_fmas_f32 v224, v224, v225, v227
	v_div_fixup_f32 v2, v224, v6, v2
	v_div_scale_f32 v231, vcc, v3, v7, v3
	v_mul_f32_e32 v232, v231, v230
	v_fma_f32 v233, -v229, v232, v231
	v_fmac_f32_e32 v232, v233, v230
	v_fma_f32 v229, -v229, v232, v231
	v_div_fmas_f32 v229, v229, v230, v232
	v_div_fixup_f32 v3, v229, v7, v3
	s_waitcnt vmcnt(15)
; #define PG8_BAR __builtin_amdgcn_s_barrier()
; template <class Epi>
; DI void gemm_phase(LAS unsigned char* lds, const int tid, const Gemm g, const StaticOrder& S, const Epi& E) {
;     ...
;         if (wr == 0) PG8_BAR;
;         E(acc, cur, wr, wc, fr, fq);
;         if (!has_next) break;
; #pragma unroll
;         for (int a = 0; a < 2; ++a)
; #pragma unroll
;             for (int b = 0; b < 2; ++b)
; #pragma unroll
;                 for (int m = 0; m < 4; ++m)
; #pragma unroll
;                     for (int n = 0; n < 2; ++n) acc[a][b][m][n] = (f32x4){0.f, 0.f, 0.f, 0.f};
;         cur = nxt; cA = nA; cB = nB; ++ui;
;         if (wr == 1) PG8_BAR;
;     DI void operator()(const f32x4 (&acc)[2][2][4][2], const Unit& u, int wr, int wc, int fr, int fq) const {
;     ...
;                     const f32x4 x0 = *(const f32x4*)(src + off); const f32x4 za = acc[ai][bj][m][0], zb = acc[ai][bj][m][1]; f32x4 o;
; #pragma unroll
;                     for (int q = 0; q < 4; ++q) o[q] = za[q] / (1.f + __expf(-zb[q]));
;                     *(f32x4*)(dst + off) = x0 + g0 * o; }
	v_pk_fma_f32 v[124:125], v[124:125], v[216:217], v[176:177]
	v_pk_fma_f32 v[126:127], v[126:127], v[218:219], v[178:179]
	global_store_dwordx4 v[234:235], v[124:127], off nt
	s_waitcnt vmcnt(15)
	v_pk_fma_f32 v[56:57], v[56:57], v[220:221], v[180:181]
	v_pk_fma_f32 v[58:59], v[58:59], v[222:223], v[182:183]
	global_store_dwordx4 v[234:235], v[56:59], off offset:256 nt
	v_lshl_add_u64 v[234:235], v[234:235], 0, s[12:13]
	s_waitcnt vmcnt(15)
	v_pk_fma_f32 v[116:117], v[116:117], v[216:217], v[184:185]
	v_pk_fma_f32 v[118:119], v[118:119], v[218:219], v[186:187]
	global_store_dwordx4 v[234:235], v[116:119], off nt
	s_waitcnt vmcnt(15)
	v_pk_fma_f32 v[48:49], v[48:49], v[220:221], v[188:189]
	v_pk_fma_f32 v[50:51], v[50:51], v[222:223], v[190:191]
	global_store_dwordx4 v[234:235], v[48:51], off offset:256 nt
	v_lshl_add_u64 v[234:235], v[234:235], 0, s[12:13]
	s_waitcnt vmcnt(15)
	v_pk_fma_f32 v[108:109], v[108:109], v[216:217], v[192:193]
	v_pk_fma_f32 v[110:111], v[110:111], v[218:219], v[194:195]
	global_store_dwordx4 v[234:235], v[108:111], off nt
	s_waitcnt vmcnt(15)
	v_pk_fma_f32 v[40:41], v[40:41], v[220:221], v[196:197]
	v_pk_fma_f32 v[42:43], v[42:43], v[222:223], v[198:199]
	global_store_dwordx4 v[234:235], v[40:43], off offset:256 nt
	v_lshl_add_u64 v[234:235], v[234:235], 0, s[12:13]
	s_waitcnt vmcnt(15)
	v_pk_fma_f32 v[100:101], v[100:101], v[216:217], v[200:201]
	v_pk_fma_f32 v[102:103], v[102:103], v[218:219], v[202:203]
	global_store_dwordx4 v[234:235], v[100:103], off nt
	s_waitcnt vmcnt(15)
	v_pk_fma_f32 v[32:33], v[32:33], v[220:221], v[204:205]
	v_pk_fma_f32 v[34:35], v[34:35], v[222:223], v[206:207]
	global_store_dwordx4 v[234:235], v[32:35], off offset:256 nt
	v_lshl_add_u64 v[234:235], v[234:235], 0, s[12:13]
	v_lshl_add_u64 v[234:235], v[234:235], 0, s[12:13]
	v_lshl_add_u64 v[234:235], v[234:235], 0, s[12:13]
	v_lshl_add_u64 v[234:235], v[234:235], 0, s[12:13]
	v_lshl_add_u64 v[234:235], v[234:235], 0, s[12:13]
	s_waitcnt vmcnt(15)
	v_pk_fma_f32 v[92:93], v[92:93], v[216:217], v[128:129]
	v_pk_fma_f32 v[94:95], v[94:95], v[218:219], v[130:131]
	global_store_dwordx4 v[234:235], v[92:95], off nt
	s_waitcnt vmcnt(15)
	v_pk_fma_f32 v[24:25], v[24:25], v[220:221], v[60:61]
	v_pk_fma_f32 v[26:27], v[26:27], v[222:223], v[62:63]
	global_store_dwordx4 v[234:235], v[24:27], off offset:256 nt
	v_lshl_add_u64 v[234:235], v[234:235], 0, s[12:13]
	s_waitcnt vmcnt(15)
	v_pk_fma_f32 v[80:81], v[80:81], v[216:217], v[120:121]
	v_pk_fma_f32 v[82:83], v[82:83], v[218:219], v[122:123]
	global_store_dwordx4 v[234:235], v[80:83], off nt
	s_waitcnt vmcnt(15)
	v_pk_fma_f32 v[16:17], v[16:17], v[220:221], v[52:53]
	v_pk_fma_f32 v[18:19], v[18:19], v[222:223], v[54:55]
	global_store_dwordx4 v[234:235], v[16:19], off offset:256 nt
	v_lshl_add_u64 v[234:235], v[234:235], 0, s[12:13]
	s_waitcnt vmcnt(15)
	v_pk_fma_f32 v[72:73], v[72:73], v[216:217], v[112:113]
	v_pk_fma_f32 v[74:75], v[74:75], v[218:219], v[114:115]
	global_store_dwordx4 v[234:235], v[72:75], off nt
	s_waitcnt vmcnt(15)
	v_pk_fma_f32 v[8:9], v[8:9], v[220:221], v[44:45]
	v_pk_fma_f32 v[10:11], v[10:11], v[222:223], v[46:47]
	global_store_dwordx4 v[234:235], v[8:11], off offset:256 nt
	v_lshl_add_u64 v[234:235], v[234:235], 0, s[12:13]
	s_waitcnt vmcnt(15)
	v_pk_fma_f32 v[64:65], v[64:65], v[216:217], v[104:105]
	v_pk_fma_f32 v[66:67], v[66:67], v[218:219], v[106:107]
	global_store_dwordx4 v[234:235], v[64:67], off nt
	s_waitcnt vmcnt(15)
	v_pk_fma_f32 v[0:1], v[0:1], v[220:221], v[36:37]
	v_pk_fma_f32 v[2:3], v[2:3], v[222:223], v[38:39]
	s_mov_b64 s[26:27], -1
	s_and_b64 vcc, exec, s[38:39]
	global_store_dwordx4 v[234:235], v[0:3], off offset:256 nt
	s_cbranch_vccnz .LBB0_653
	s_andn2_b64 vcc, exec, s[6:7]
	s_cbranch_vccnz .LBB0_652
	s_barrier
	s_branch .LBB0_652
